# w_o residual epilogue fused with the following rmsnorm+modulate, bf16 result stored 16 bytes per lane after a lane-pair exchange; on the final-norm fusion
# speedup vs baseline: 1.0058x; 1.0058x over previous
.Lfn_meet_p11:
	s_or_b64 exec, exec, s[22:23]
	s_barrier
	global_load_dwordx4 v[220:223], v144, s[44:45] sc1
	global_load_dwordx4 v[224:227], v144, s[44:45] offset:256 sc1
	global_load_dwordx4 v[232:235], v144, s[44:45] offset:512 sc1
	global_load_dwordx4 v[236:239], v144, s[44:45] offset:768 sc1
	global_load_dwordx4 v[240:243], v144, s[44:45] offset:2048 sc1
	global_load_dwordx4 v[244:247], v144, s[44:45] offset:2304 sc1
	global_load_dwordx4 v[156:159], v144, s[44:45] offset:2560 sc1
	global_load_dwordx4 v[160:163], v144, s[44:45] offset:2816 sc1
	s_waitcnt vmcnt(0)
	v_add_f32_e32 v248, v220, v221
	v_add_f32_e32 v249, v222, v223
	v_add_f32_e32 v146, v248, v249
	v_add_f32_e32 v248, v224, v225
	v_add_f32_e32 v249, v226, v227
	v_add_f32_e32 v147, v248, v249
	v_add_f32_e32 v248, v232, v233
	v_add_f32_e32 v249, v234, v235
	v_add_f32_e32 v148, v248, v249
	v_add_f32_e32 v248, v236, v237
	v_add_f32_e32 v249, v238, v239
	v_add_f32_e32 v149, v248, v249
	v_add_f32_e32 v248, v240, v241
	v_add_f32_e32 v249, v242, v243
	v_add_f32_e32 v150, v248, v249
	v_add_f32_e32 v248, v244, v245
	v_add_f32_e32 v249, v246, v247
	v_add_f32_e32 v151, v248, v249
	v_add_f32_e32 v248, v156, v157
	v_add_f32_e32 v249, v158, v159
	v_add_f32_e32 v152, v248, v249
	v_add_f32_e32 v248, v160, v161
	v_add_f32_e32 v249, v162, v163
	v_add_f32_e32 v153, v248, v249
	global_load_dwordx4 v[180:183], v136, s[42:43]
	global_load_dwordx4 v[184:187], v136, s[42:43] offset:64
	global_load_dwordx4 v[188:191], v136, s[42:43] offset:512
	global_load_dwordx4 v[192:195], v136, s[42:43] offset:576
	global_load_dwordx4 v[220:223], v136, s[70:71]
	global_load_dwordx4 v[224:227], v136, s[70:71] offset:64
	global_load_dwordx4 v[232:235], v136, s[70:71] offset:512
	global_load_dwordx4 v[236:239], v136, s[70:71] offset:576
	global_load_dwordx4 v[240:243], v136, s[72:73]
	global_load_dwordx4 v[244:247], v136, s[72:73] offset:64
	global_load_dwordx4 v[156:159], v136, s[72:73] offset:512
	global_load_dwordx4 v[160:163], v136, s[72:73] offset:576
	v_mov_b32_e32 v228, 0x358637bd
	v_mov_b32_e32 v229, 0x260
	s_mov_b32 s14, 0xf800000
	v_fmamk_f32 v146, v146, 0x3a800000, v228
	v_mul_f32_e32 v164, 0x4f800000, v146
	v_cmp_gt_f32_e32 vcc, s14, v146
	s_nop 1
	v_cndmask_b32_e32 v146, v146, v164, vcc
	v_sqrt_f32_e32 v165, v146
	s_nop 1
	v_add_u32_e32 v166, -1, v165
	v_add_u32_e32 v167, 1, v165
	v_fma_f32 v204, -v166, v165, v146
	v_fma_f32 v205, -v167, v165, v146
	v_cmp_ge_f32_e64 s[26:27], 0, v204
	s_nop 1
	v_cndmask_b32_e64 v165, v165, v166, s[26:27]
	v_cmp_lt_f32_e64 s[26:27], 0, v205
	s_nop 1
	v_cndmask_b32_e64 v165, v165, v167, s[26:27]
	v_mul_f32_e32 v166, 0x37800000, v165
	v_cndmask_b32_e32 v165, v165, v166, vcc
	v_cmp_class_f32_e32 vcc, v146, v229
	s_nop 1
	v_cndmask_b32_e32 v146, v165, v146, vcc
	v_div_scale_f32 v164, s[26:27], v146, v146, 1.0
	v_rcp_f32_e32 v165, v164
	v_div_scale_f32 v166, vcc, 1.0, v146, 1.0
	v_fma_f32 v167, -v164, v165, 1.0
	v_fmac_f32_e32 v165, v167, v165
	v_mul_f32_e32 v167, v166, v165
	v_fma_f32 v204, -v164, v167, v166
	v_fmac_f32_e32 v167, v204, v165
	v_fma_f32 v164, -v164, v167, v166
	v_div_fmas_f32 v167, v164, v165, v167
	v_div_fixup_f32 v196, v167, v146, 1.0
	v_fmamk_f32 v147, v147, 0x3a800000, v228
	v_mul_f32_e32 v164, 0x4f800000, v147
	v_cmp_gt_f32_e32 vcc, s14, v147
	s_nop 1
	v_cndmask_b32_e32 v147, v147, v164, vcc
	v_sqrt_f32_e32 v165, v147
	s_nop 1
	v_add_u32_e32 v166, -1, v165
	v_add_u32_e32 v167, 1, v165
	v_fma_f32 v204, -v166, v165, v147
	v_fma_f32 v205, -v167, v165, v147
	v_cmp_ge_f32_e64 s[26:27], 0, v204
	s_nop 1
	v_cndmask_b32_e64 v165, v165, v166, s[26:27]
	v_cmp_lt_f32_e64 s[26:27], 0, v205
	s_nop 1
	v_cndmask_b32_e64 v165, v165, v167, s[26:27]
	v_mul_f32_e32 v166, 0x37800000, v165
	v_cndmask_b32_e32 v165, v165, v166, vcc
	v_cmp_class_f32_e32 vcc, v147, v229
	s_nop 1
	v_cndmask_b32_e32 v147, v165, v147, vcc
	v_div_scale_f32 v164, s[26:27], v147, v147, 1.0
	v_rcp_f32_e32 v165, v164
	v_div_scale_f32 v166, vcc, 1.0, v147, 1.0
	v_fma_f32 v167, -v164, v165, 1.0
	v_fmac_f32_e32 v165, v167, v165
	v_mul_f32_e32 v167, v166, v165
	v_fma_f32 v204, -v164, v167, v166
	v_fmac_f32_e32 v167, v204, v165
	v_fma_f32 v164, -v164, v167, v166
	v_div_fmas_f32 v167, v164, v165, v167
	v_div_fixup_f32 v198, v167, v147, 1.0
	v_fmamk_f32 v148, v148, 0x3a800000, v228
	v_mul_f32_e32 v164, 0x4f800000, v148
	v_cmp_gt_f32_e32 vcc, s14, v148
	s_nop 1
	v_cndmask_b32_e32 v148, v148, v164, vcc
	v_sqrt_f32_e32 v165, v148
	s_nop 1
	v_add_u32_e32 v166, -1, v165
	v_add_u32_e32 v167, 1, v165
	v_fma_f32 v204, -v166, v165, v148
	v_fma_f32 v205, -v167, v165, v148
	v_cmp_ge_f32_e64 s[26:27], 0, v204
	s_nop 1
	v_cndmask_b32_e64 v165, v165, v166, s[26:27]
	v_cmp_lt_f32_e64 s[26:27], 0, v205
	s_nop 1
	v_cndmask_b32_e64 v165, v165, v167, s[26:27]
	v_mul_f32_e32 v166, 0x37800000, v165
	v_cndmask_b32_e32 v165, v165, v166, vcc
	v_cmp_class_f32_e32 vcc, v148, v229
	s_nop 1
	v_cndmask_b32_e32 v148, v165, v148, vcc
	v_div_scale_f32 v164, s[26:27], v148, v148, 1.0
	v_rcp_f32_e32 v165, v164
	v_div_scale_f32 v166, vcc, 1.0, v148, 1.0
	v_fma_f32 v167, -v164, v165, 1.0
	v_fmac_f32_e32 v165, v167, v165
	v_mul_f32_e32 v167, v166, v165
	v_fma_f32 v204, -v164, v167, v166
	v_fmac_f32_e32 v167, v204, v165
	v_fma_f32 v164, -v164, v167, v166
	v_div_fmas_f32 v167, v164, v165, v167
	v_div_fixup_f32 v200, v167, v148, 1.0
	v_fmamk_f32 v149, v149, 0x3a800000, v228
	v_mul_f32_e32 v164, 0x4f800000, v149
	v_cmp_gt_f32_e32 vcc, s14, v149
	s_nop 1
	v_cndmask_b32_e32 v149, v149, v164, vcc
	v_sqrt_f32_e32 v165, v149
	s_nop 1
	v_add_u32_e32 v166, -1, v165
	v_add_u32_e32 v167, 1, v165
	v_fma_f32 v204, -v166, v165, v149
	v_fma_f32 v205, -v167, v165, v149
	v_cmp_ge_f32_e64 s[26:27], 0, v204
	s_nop 1
	v_cndmask_b32_e64 v165, v165, v166, s[26:27]
	v_cmp_lt_f32_e64 s[26:27], 0, v205
	s_nop 1
	v_cndmask_b32_e64 v165, v165, v167, s[26:27]
	v_mul_f32_e32 v166, 0x37800000, v165
	v_cndmask_b32_e32 v165, v165, v166, vcc
	v_cmp_class_f32_e32 vcc, v149, v229
	s_nop 1
	v_cndmask_b32_e32 v149, v165, v149, vcc
	v_div_scale_f32 v164, s[26:27], v149, v149, 1.0
	v_rcp_f32_e32 v165, v164
	v_div_scale_f32 v166, vcc, 1.0, v149, 1.0
	v_fma_f32 v167, -v164, v165, 1.0
	v_fmac_f32_e32 v165, v167, v165
	v_mul_f32_e32 v167, v166, v165
	v_fma_f32 v204, -v164, v167, v166
	v_fmac_f32_e32 v167, v204, v165
	v_fma_f32 v164, -v164, v167, v166
	v_div_fmas_f32 v167, v164, v165, v167
	v_div_fixup_f32 v202, v167, v149, 1.0
	v_fmamk_f32 v150, v150, 0x3a800000, v228
	v_mul_f32_e32 v164, 0x4f800000, v150
	v_cmp_gt_f32_e32 vcc, s14, v150
	s_nop 1
	v_cndmask_b32_e32 v150, v150, v164, vcc
	v_sqrt_f32_e32 v165, v150
	s_nop 1
	v_add_u32_e32 v166, -1, v165
	v_add_u32_e32 v167, 1, v165
	v_fma_f32 v204, -v166, v165, v150
	v_fma_f32 v205, -v167, v165, v150
	v_cmp_ge_f32_e64 s[26:27], 0, v204
	s_nop 1
	v_cndmask_b32_e64 v165, v165, v166, s[26:27]
	v_cmp_lt_f32_e64 s[26:27], 0, v205
	s_nop 1
	v_cndmask_b32_e64 v165, v165, v167, s[26:27]
	v_mul_f32_e32 v166, 0x37800000, v165
	v_cndmask_b32_e32 v165, v165, v166, vcc
	v_cmp_class_f32_e32 vcc, v150, v229
	s_nop 1
	v_cndmask_b32_e32 v150, v165, v150, vcc
	v_div_scale_f32 v164, s[26:27], v150, v150, 1.0
	v_rcp_f32_e32 v165, v164
	v_div_scale_f32 v166, vcc, 1.0, v150, 1.0
	v_fma_f32 v167, -v164, v165, 1.0
	v_fmac_f32_e32 v165, v167, v165
	v_mul_f32_e32 v167, v166, v165
	v_fma_f32 v204, -v164, v167, v166
	v_fmac_f32_e32 v167, v204, v165
	v_fma_f32 v164, -v164, v167, v166
	v_div_fmas_f32 v167, v164, v165, v167
	v_div_fixup_f32 v212, v167, v150, 1.0
	v_fmamk_f32 v151, v151, 0x3a800000, v228
	v_mul_f32_e32 v164, 0x4f800000, v151
	v_cmp_gt_f32_e32 vcc, s14, v151
	s_nop 1
	v_cndmask_b32_e32 v151, v151, v164, vcc
	v_sqrt_f32_e32 v165, v151
	s_nop 1
	v_add_u32_e32 v166, -1, v165
	v_add_u32_e32 v167, 1, v165
	v_fma_f32 v204, -v166, v165, v151
	v_fma_f32 v205, -v167, v165, v151
	v_cmp_ge_f32_e64 s[26:27], 0, v204
	s_nop 1
	v_cndmask_b32_e64 v165, v165, v166, s[26:27]
	v_cmp_lt_f32_e64 s[26:27], 0, v205
	s_nop 1
	v_cndmask_b32_e64 v165, v165, v167, s[26:27]
	v_mul_f32_e32 v166, 0x37800000, v165
	v_cndmask_b32_e32 v165, v165, v166, vcc
	v_cmp_class_f32_e32 vcc, v151, v229
	s_nop 1
	v_cndmask_b32_e32 v151, v165, v151, vcc
	v_div_scale_f32 v164, s[26:27], v151, v151, 1.0
	v_rcp_f32_e32 v165, v164
	v_div_scale_f32 v166, vcc, 1.0, v151, 1.0
	v_fma_f32 v167, -v164, v165, 1.0
	v_fmac_f32_e32 v165, v167, v165
	v_mul_f32_e32 v167, v166, v165
	v_fma_f32 v204, -v164, v167, v166
	v_fmac_f32_e32 v167, v204, v165
	v_fma_f32 v164, -v164, v167, v166
	v_div_fmas_f32 v167, v164, v165, v167
	v_div_fixup_f32 v214, v167, v151, 1.0
	v_fmamk_f32 v152, v152, 0x3a800000, v228
	v_mul_f32_e32 v164, 0x4f800000, v152
	v_cmp_gt_f32_e32 vcc, s14, v152
	s_nop 1
	v_cndmask_b32_e32 v152, v152, v164, vcc
	v_sqrt_f32_e32 v165, v152
	s_nop 1
	v_add_u32_e32 v166, -1, v165
	v_add_u32_e32 v167, 1, v165
	v_fma_f32 v204, -v166, v165, v152
	v_fma_f32 v205, -v167, v165, v152
	v_cmp_ge_f32_e64 s[26:27], 0, v204
	s_nop 1
	v_cndmask_b32_e64 v165, v165, v166, s[26:27]
	v_cmp_lt_f32_e64 s[26:27], 0, v205
	s_nop 1
	v_cndmask_b32_e64 v165, v165, v167, s[26:27]
	v_mul_f32_e32 v166, 0x37800000, v165
	v_cndmask_b32_e32 v165, v165, v166, vcc
	v_cmp_class_f32_e32 vcc, v152, v229
	s_nop 1
	v_cndmask_b32_e32 v152, v165, v152, vcc
	v_div_scale_f32 v164, s[26:27], v152, v152, 1.0
	v_rcp_f32_e32 v165, v164
	v_div_scale_f32 v166, vcc, 1.0, v152, 1.0
	v_fma_f32 v167, -v164, v165, 1.0
	v_fmac_f32_e32 v165, v167, v165
	v_mul_f32_e32 v167, v166, v165
	v_fma_f32 v204, -v164, v167, v166
	v_fmac_f32_e32 v167, v204, v165
	v_fma_f32 v164, -v164, v167, v166
	v_div_fmas_f32 v167, v164, v165, v167
	v_div_fixup_f32 v216, v167, v152, 1.0
	v_fmamk_f32 v153, v153, 0x3a800000, v228
	v_mul_f32_e32 v164, 0x4f800000, v153
	v_cmp_gt_f32_e32 vcc, s14, v153
	s_nop 1
	v_cndmask_b32_e32 v153, v153, v164, vcc
	v_sqrt_f32_e32 v165, v153
	s_nop 1
	v_add_u32_e32 v166, -1, v165
	v_add_u32_e32 v167, 1, v165
	v_fma_f32 v204, -v166, v165, v153
	v_fma_f32 v205, -v167, v165, v153
	v_cmp_ge_f32_e64 s[26:27], 0, v204
	s_nop 1
	v_cndmask_b32_e64 v165, v165, v166, s[26:27]
	v_cmp_lt_f32_e64 s[26:27], 0, v205
	s_nop 1
	v_cndmask_b32_e64 v165, v165, v167, s[26:27]
	v_mul_f32_e32 v166, 0x37800000, v165
	v_cndmask_b32_e32 v165, v165, v166, vcc
	v_cmp_class_f32_e32 vcc, v153, v229
	s_nop 1
	v_cndmask_b32_e32 v153, v165, v153, vcc
	v_div_scale_f32 v164, s[26:27], v153, v153, 1.0
	v_rcp_f32_e32 v165, v164
	v_div_scale_f32 v166, vcc, 1.0, v153, 1.0
	v_fma_f32 v167, -v164, v165, 1.0
	v_fmac_f32_e32 v165, v167, v165
	v_mul_f32_e32 v167, v166, v165
	v_fma_f32 v204, -v164, v167, v166
	v_fmac_f32_e32 v167, v204, v165
	v_fma_f32 v164, -v164, v167, v166
	v_div_fmas_f32 v167, v164, v165, v167
	v_div_fixup_f32 v218, v167, v153, 1.0
	v_lshrrev_b32_e32 v128, 1, v128
	v_lshrrev_b32_e32 v129, 1, v129
	v_lshrrev_b32_e32 v130, 1, v130
	v_lshrrev_b32_e32 v131, 1, v131
	v_lshrrev_b32_e32 v132, 1, v132
	v_lshrrev_b32_e32 v133, 1, v133
	v_lshrrev_b32_e32 v134, 1, v134
	v_lshrrev_b32_e32 v135, 1, v135
	s_waitcnt vmcnt(0)
	v_pk_add_f32 v[220:221], v[220:221], 1.0 op_sel_hi:[1,0]
	v_pk_add_f32 v[222:223], v[222:223], 1.0 op_sel_hi:[1,0]
	v_pk_add_f32 v[224:225], v[224:225], 1.0 op_sel_hi:[1,0]
	v_pk_add_f32 v[226:227], v[226:227], 1.0 op_sel_hi:[1,0]
	v_pk_add_f32 v[232:233], v[232:233], 1.0 op_sel_hi:[1,0]
	v_pk_add_f32 v[234:235], v[234:235], 1.0 op_sel_hi:[1,0]
	v_pk_add_f32 v[236:237], v[236:237], 1.0 op_sel_hi:[1,0]
	v_pk_add_f32 v[238:239], v[238:239], 1.0 op_sel_hi:[1,0]
	v_and_b32_e32 v144, 16, v230
	v_cmp_ne_u32_e64 s[74:75], 0, v144
	v_mov_b32_e32 v145, 24
	s_nop 0
	v_cndmask_b32_e64 v144, 0, v145, s[74:75]
	v_add_u32_e32 v128, v128, v144
	v_add_u32_e32 v129, v129, v144
	v_add_u32_e32 v130, v130, v144
	v_add_u32_e32 v131, v131, v144
	v_add_u32_e32 v132, v132, v144
	v_add_u32_e32 v133, v133, v144
	v_add_u32_e32 v134, v134, v144
	v_add_u32_e32 v135, v135, v144
	v_pk_mul_f32 v[124:125], v[124:125], v[196:197] op_sel_hi:[1,0]
	v_pk_mul_f32 v[126:127], v[126:127], v[196:197] op_sel_hi:[1,0]
	v_pk_mul_f32 v[124:125], v[180:181], v[124:125]
	v_pk_mul_f32 v[126:127], v[182:183], v[126:127]
	v_pk_fma_f32 v[124:125], v[220:221], v[124:125], v[240:241]
	v_pk_fma_f32 v[126:127], v[222:223], v[126:127], v[242:243]
	v_cvt_pk_bf16_f32 v124, v124, v125
	v_cvt_pk_bf16_f32 v125, v126, v127
	v_pk_mul_f32 v[100:101], v[100:101], v[196:197] op_sel_hi:[1,0]
	v_pk_mul_f32 v[102:103], v[102:103], v[196:197] op_sel_hi:[1,0]
	v_pk_mul_f32 v[100:101], v[184:185], v[100:101]
	v_pk_mul_f32 v[102:103], v[186:187], v[102:103]
	v_pk_fma_f32 v[100:101], v[224:225], v[100:101], v[244:245]
	v_pk_fma_f32 v[102:103], v[226:227], v[102:103], v[246:247]
	v_cvt_pk_bf16_f32 v100, v100, v101
	v_cvt_pk_bf16_f32 v101, v102, v103
	v_pk_mul_f32 v[68:69], v[68:69], v[196:197] op_sel_hi:[1,0]
	v_pk_mul_f32 v[70:71], v[70:71], v[196:197] op_sel_hi:[1,0]
	v_pk_mul_f32 v[68:69], v[188:189], v[68:69]
	v_pk_mul_f32 v[70:71], v[190:191], v[70:71]
	v_pk_fma_f32 v[68:69], v[232:233], v[68:69], v[156:157]
	v_pk_fma_f32 v[70:71], v[234:235], v[70:71], v[158:159]
	v_cvt_pk_bf16_f32 v68, v68, v69
	v_cvt_pk_bf16_f32 v69, v70, v71
	v_pk_mul_f32 v[44:45], v[44:45], v[196:197] op_sel_hi:[1,0]
	v_pk_mul_f32 v[46:47], v[46:47], v[196:197] op_sel_hi:[1,0]
	v_pk_mul_f32 v[44:45], v[192:193], v[44:45]
	v_pk_mul_f32 v[46:47], v[194:195], v[46:47]
	v_pk_fma_f32 v[44:45], v[236:237], v[44:45], v[160:161]
	v_pk_fma_f32 v[46:47], v[238:239], v[46:47], v[162:163]
	v_cvt_pk_bf16_f32 v44, v44, v45
	v_cvt_pk_bf16_f32 v45, v46, v47
	v_cndmask_b32_e64 v146, v100, v124, s[74:75]
	v_cndmask_b32_e64 v147, v101, v125, s[74:75]
	ds_bpermute_b32 v148, v137, v146
	ds_bpermute_b32 v149, v137, v147
	v_cndmask_b32_e64 v150, v44, v68, s[74:75]
	v_cndmask_b32_e64 v151, v45, v69, s[74:75]
	ds_bpermute_b32 v152, v137, v150
	ds_bpermute_b32 v153, v137, v151
	s_waitcnt lgkmcnt(0)
	v_cndmask_b32_e64 v126, v148, v100, s[74:75]
	v_cndmask_b32_e64 v127, v149, v101, s[74:75]
	v_cndmask_b32_e64 v124, v124, v148, s[74:75]
	v_cndmask_b32_e64 v125, v125, v149, s[74:75]
	global_store_dwordx4 v128, v[124:127], s[68:69]
	v_cndmask_b32_e64 v70, v152, v44, s[74:75]
	v_cndmask_b32_e64 v71, v153, v45, s[74:75]
	v_cndmask_b32_e64 v68, v68, v152, s[74:75]
	v_cndmask_b32_e64 v69, v69, v153, s[74:75]
	global_store_dwordx4 v128, v[68:71], s[68:69] offset:256
	v_pk_mul_f32 v[120:121], v[120:121], v[198:199] op_sel_hi:[1,0]
	v_pk_mul_f32 v[122:123], v[122:123], v[198:199] op_sel_hi:[1,0]
	v_pk_mul_f32 v[120:121], v[180:181], v[120:121]
	v_pk_mul_f32 v[122:123], v[182:183], v[122:123]
	v_pk_fma_f32 v[120:121], v[220:221], v[120:121], v[240:241]
	v_pk_fma_f32 v[122:123], v[222:223], v[122:123], v[242:243]
	v_cvt_pk_bf16_f32 v120, v120, v121
	v_cvt_pk_bf16_f32 v121, v122, v123
	v_pk_mul_f32 v[96:97], v[96:97], v[198:199] op_sel_hi:[1,0]
	v_pk_mul_f32 v[98:99], v[98:99], v[198:199] op_sel_hi:[1,0]
	v_pk_mul_f32 v[96:97], v[184:185], v[96:97]
	v_pk_mul_f32 v[98:99], v[186:187], v[98:99]
	v_pk_fma_f32 v[96:97], v[224:225], v[96:97], v[244:245]
	v_pk_fma_f32 v[98:99], v[226:227], v[98:99], v[246:247]
	v_cvt_pk_bf16_f32 v96, v96, v97
	v_cvt_pk_bf16_f32 v97, v98, v99
	v_pk_mul_f32 v[64:65], v[64:65], v[198:199] op_sel_hi:[1,0]
	v_pk_mul_f32 v[66:67], v[66:67], v[198:199] op_sel_hi:[1,0]
	v_pk_mul_f32 v[64:65], v[188:189], v[64:65]
	v_pk_mul_f32 v[66:67], v[190:191], v[66:67]
	v_pk_fma_f32 v[64:65], v[232:233], v[64:65], v[156:157]
	v_pk_fma_f32 v[66:67], v[234:235], v[66:67], v[158:159]
	v_cvt_pk_bf16_f32 v64, v64, v65
	v_cvt_pk_bf16_f32 v65, v66, v67
	v_pk_mul_f32 v[36:37], v[36:37], v[198:199] op_sel_hi:[1,0]
	v_pk_mul_f32 v[38:39], v[38:39], v[198:199] op_sel_hi:[1,0]
	v_pk_mul_f32 v[36:37], v[192:193], v[36:37]
	v_pk_mul_f32 v[38:39], v[194:195], v[38:39]
	v_pk_fma_f32 v[36:37], v[236:237], v[36:37], v[160:161]
	v_pk_fma_f32 v[38:39], v[238:239], v[38:39], v[162:163]
	v_cvt_pk_bf16_f32 v36, v36, v37
	v_cvt_pk_bf16_f32 v37, v38, v39
	v_cndmask_b32_e64 v146, v96, v120, s[74:75]
	v_cndmask_b32_e64 v147, v97, v121, s[74:75]
	ds_bpermute_b32 v148, v137, v146
	ds_bpermute_b32 v149, v137, v147
	v_cndmask_b32_e64 v150, v36, v64, s[74:75]
	v_cndmask_b32_e64 v151, v37, v65, s[74:75]
	ds_bpermute_b32 v152, v137, v150
	ds_bpermute_b32 v153, v137, v151
	s_waitcnt lgkmcnt(0)
	v_cndmask_b32_e64 v122, v148, v96, s[74:75]
	v_cndmask_b32_e64 v123, v149, v97, s[74:75]
	v_cndmask_b32_e64 v120, v120, v148, s[74:75]
	v_cndmask_b32_e64 v121, v121, v149, s[74:75]
	global_store_dwordx4 v129, v[120:123], s[68:69]
	v_cndmask_b32_e64 v66, v152, v36, s[74:75]
	v_cndmask_b32_e64 v67, v153, v37, s[74:75]
	v_cndmask_b32_e64 v64, v64, v152, s[74:75]
	v_cndmask_b32_e64 v65, v65, v153, s[74:75]
	global_store_dwordx4 v129, v[64:67], s[68:69] offset:256
	v_pk_mul_f32 v[116:117], v[116:117], v[200:201] op_sel_hi:[1,0]
	v_pk_mul_f32 v[118:119], v[118:119], v[200:201] op_sel_hi:[1,0]
	v_pk_mul_f32 v[116:117], v[180:181], v[116:117]
	v_pk_mul_f32 v[118:119], v[182:183], v[118:119]
	v_pk_fma_f32 v[116:117], v[220:221], v[116:117], v[240:241]
	v_pk_fma_f32 v[118:119], v[222:223], v[118:119], v[242:243]
	v_cvt_pk_bf16_f32 v116, v116, v117
	v_cvt_pk_bf16_f32 v117, v118, v119
	v_pk_mul_f32 v[88:89], v[88:89], v[200:201] op_sel_hi:[1,0]
	v_pk_mul_f32 v[90:91], v[90:91], v[200:201] op_sel_hi:[1,0]
	v_pk_mul_f32 v[88:89], v[184:185], v[88:89]
	v_pk_mul_f32 v[90:91], v[186:187], v[90:91]
	v_pk_fma_f32 v[88:89], v[224:225], v[88:89], v[244:245]
	v_pk_fma_f32 v[90:91], v[226:227], v[90:91], v[246:247]
	v_cvt_pk_bf16_f32 v88, v88, v89
	v_cvt_pk_bf16_f32 v89, v90, v91
	v_pk_mul_f32 v[52:53], v[52:53], v[200:201] op_sel_hi:[1,0]
	v_pk_mul_f32 v[54:55], v[54:55], v[200:201] op_sel_hi:[1,0]
	v_pk_mul_f32 v[52:53], v[188:189], v[52:53]
	v_pk_mul_f32 v[54:55], v[190:191], v[54:55]
	v_pk_fma_f32 v[52:53], v[232:233], v[52:53], v[156:157]
	v_pk_fma_f32 v[54:55], v[234:235], v[54:55], v[158:159]
	v_cvt_pk_bf16_f32 v52, v52, v53
	v_cvt_pk_bf16_f32 v53, v54, v55
	v_pk_mul_f32 v[28:29], v[28:29], v[200:201] op_sel_hi:[1,0]
	v_pk_mul_f32 v[30:31], v[30:31], v[200:201] op_sel_hi:[1,0]
	v_pk_mul_f32 v[28:29], v[192:193], v[28:29]
	v_pk_mul_f32 v[30:31], v[194:195], v[30:31]
	v_pk_fma_f32 v[28:29], v[236:237], v[28:29], v[160:161]
	v_pk_fma_f32 v[30:31], v[238:239], v[30:31], v[162:163]
	v_cvt_pk_bf16_f32 v28, v28, v29
	v_cvt_pk_bf16_f32 v29, v30, v31
	v_cndmask_b32_e64 v146, v88, v116, s[74:75]
	v_cndmask_b32_e64 v147, v89, v117, s[74:75]
	ds_bpermute_b32 v148, v137, v146
	ds_bpermute_b32 v149, v137, v147
	v_cndmask_b32_e64 v150, v28, v52, s[74:75]
	v_cndmask_b32_e64 v151, v29, v53, s[74:75]
	ds_bpermute_b32 v152, v137, v150
	ds_bpermute_b32 v153, v137, v151
	s_waitcnt lgkmcnt(0)
	v_cndmask_b32_e64 v118, v148, v88, s[74:75]
	v_cndmask_b32_e64 v119, v149, v89, s[74:75]
	v_cndmask_b32_e64 v116, v116, v148, s[74:75]
	v_cndmask_b32_e64 v117, v117, v149, s[74:75]
	global_store_dwordx4 v130, v[116:119], s[68:69]
	v_cndmask_b32_e64 v54, v152, v28, s[74:75]
	v_cndmask_b32_e64 v55, v153, v29, s[74:75]
	v_cndmask_b32_e64 v52, v52, v152, s[74:75]
	v_cndmask_b32_e64 v53, v53, v153, s[74:75]
	global_store_dwordx4 v130, v[52:55], s[68:69] offset:256
	v_pk_mul_f32 v[112:113], v[112:113], v[202:203] op_sel_hi:[1,0]
	v_pk_mul_f32 v[114:115], v[114:115], v[202:203] op_sel_hi:[1,0]
	v_pk_mul_f32 v[112:113], v[180:181], v[112:113]
	v_pk_mul_f32 v[114:115], v[182:183], v[114:115]
	v_pk_fma_f32 v[112:113], v[220:221], v[112:113], v[240:241]
	v_pk_fma_f32 v[114:115], v[222:223], v[114:115], v[242:243]
	v_cvt_pk_bf16_f32 v112, v112, v113
	v_cvt_pk_bf16_f32 v113, v114, v115
	v_pk_mul_f32 v[80:81], v[80:81], v[202:203] op_sel_hi:[1,0]
	v_pk_mul_f32 v[82:83], v[82:83], v[202:203] op_sel_hi:[1,0]
	v_pk_mul_f32 v[80:81], v[184:185], v[80:81]
	v_pk_mul_f32 v[82:83], v[186:187], v[82:83]
	v_pk_fma_f32 v[80:81], v[224:225], v[80:81], v[244:245]
	v_pk_fma_f32 v[82:83], v[226:227], v[82:83], v[246:247]
	v_cvt_pk_bf16_f32 v80, v80, v81
	v_cvt_pk_bf16_f32 v81, v82, v83
	v_pk_mul_f32 v[48:49], v[48:49], v[202:203] op_sel_hi:[1,0]
	v_pk_mul_f32 v[50:51], v[50:51], v[202:203] op_sel_hi:[1,0]
	v_pk_mul_f32 v[48:49], v[188:189], v[48:49]
	v_pk_mul_f32 v[50:51], v[190:191], v[50:51]
	v_pk_fma_f32 v[48:49], v[232:233], v[48:49], v[156:157]
	v_pk_fma_f32 v[50:51], v[234:235], v[50:51], v[158:159]
	v_cvt_pk_bf16_f32 v48, v48, v49
	v_cvt_pk_bf16_f32 v49, v50, v51
	v_pk_mul_f32 v[20:21], v[20:21], v[202:203] op_sel_hi:[1,0]
	v_pk_mul_f32 v[22:23], v[22:23], v[202:203] op_sel_hi:[1,0]
	v_pk_mul_f32 v[20:21], v[192:193], v[20:21]
	v_pk_mul_f32 v[22:23], v[194:195], v[22:23]
	v_pk_fma_f32 v[20:21], v[236:237], v[20:21], v[160:161]
	v_pk_fma_f32 v[22:23], v[238:239], v[22:23], v[162:163]
	v_cvt_pk_bf16_f32 v20, v20, v21
	v_cvt_pk_bf16_f32 v21, v22, v23
	v_cndmask_b32_e64 v146, v80, v112, s[74:75]
	v_cndmask_b32_e64 v147, v81, v113, s[74:75]
	ds_bpermute_b32 v148, v137, v146
	ds_bpermute_b32 v149, v137, v147
	v_cndmask_b32_e64 v150, v20, v48, s[74:75]
	v_cndmask_b32_e64 v151, v21, v49, s[74:75]
	ds_bpermute_b32 v152, v137, v150
	ds_bpermute_b32 v153, v137, v151
	s_waitcnt lgkmcnt(0)
	v_cndmask_b32_e64 v114, v148, v80, s[74:75]
	v_cndmask_b32_e64 v115, v149, v81, s[74:75]
	v_cndmask_b32_e64 v112, v112, v148, s[74:75]
	v_cndmask_b32_e64 v113, v113, v149, s[74:75]
	global_store_dwordx4 v131, v[112:115], s[68:69]
	v_cndmask_b32_e64 v50, v152, v20, s[74:75]
	v_cndmask_b32_e64 v51, v153, v21, s[74:75]
	v_cndmask_b32_e64 v48, v48, v152, s[74:75]
	v_cndmask_b32_e64 v49, v49, v153, s[74:75]
	global_store_dwordx4 v131, v[48:51], s[68:69] offset:256
	v_pk_mul_f32 v[108:109], v[108:109], v[212:213] op_sel_hi:[1,0]
	v_pk_mul_f32 v[110:111], v[110:111], v[212:213] op_sel_hi:[1,0]
	v_pk_mul_f32 v[108:109], v[180:181], v[108:109]
	v_pk_mul_f32 v[110:111], v[182:183], v[110:111]
	v_pk_fma_f32 v[108:109], v[220:221], v[108:109], v[240:241]
	v_pk_fma_f32 v[110:111], v[222:223], v[110:111], v[242:243]
	v_cvt_pk_bf16_f32 v108, v108, v109
	v_cvt_pk_bf16_f32 v109, v110, v111
	v_pk_mul_f32 v[76:77], v[76:77], v[212:213] op_sel_hi:[1,0]
	v_pk_mul_f32 v[78:79], v[78:79], v[212:213] op_sel_hi:[1,0]
	v_pk_mul_f32 v[76:77], v[184:185], v[76:77]
	v_pk_mul_f32 v[78:79], v[186:187], v[78:79]
	v_pk_fma_f32 v[76:77], v[224:225], v[76:77], v[244:245]
	v_pk_fma_f32 v[78:79], v[226:227], v[78:79], v[246:247]
	v_cvt_pk_bf16_f32 v76, v76, v77
	v_cvt_pk_bf16_f32 v77, v78, v79
	v_pk_mul_f32 v[40:41], v[40:41], v[212:213] op_sel_hi:[1,0]
	v_pk_mul_f32 v[42:43], v[42:43], v[212:213] op_sel_hi:[1,0]
	v_pk_mul_f32 v[40:41], v[188:189], v[40:41]
	v_pk_mul_f32 v[42:43], v[190:191], v[42:43]
	v_pk_fma_f32 v[40:41], v[232:233], v[40:41], v[156:157]
	v_pk_fma_f32 v[42:43], v[234:235], v[42:43], v[158:159]
	v_cvt_pk_bf16_f32 v40, v40, v41
	v_cvt_pk_bf16_f32 v41, v42, v43
	v_pk_mul_f32 v[12:13], v[12:13], v[212:213] op_sel_hi:[1,0]
	v_pk_mul_f32 v[14:15], v[14:15], v[212:213] op_sel_hi:[1,0]
	v_pk_mul_f32 v[12:13], v[192:193], v[12:13]
	v_pk_mul_f32 v[14:15], v[194:195], v[14:15]
	v_pk_fma_f32 v[12:13], v[236:237], v[12:13], v[160:161]
	v_pk_fma_f32 v[14:15], v[238:239], v[14:15], v[162:163]
	v_cvt_pk_bf16_f32 v12, v12, v13
	v_cvt_pk_bf16_f32 v13, v14, v15
	v_cndmask_b32_e64 v146, v76, v108, s[74:75]
	v_cndmask_b32_e64 v147, v77, v109, s[74:75]
	ds_bpermute_b32 v148, v137, v146
	ds_bpermute_b32 v149, v137, v147
	v_cndmask_b32_e64 v150, v12, v40, s[74:75]
	v_cndmask_b32_e64 v151, v13, v41, s[74:75]
	ds_bpermute_b32 v152, v137, v150
	ds_bpermute_b32 v153, v137, v151
	s_waitcnt lgkmcnt(0)
	v_cndmask_b32_e64 v110, v148, v76, s[74:75]
	v_cndmask_b32_e64 v111, v149, v77, s[74:75]
	v_cndmask_b32_e64 v108, v108, v148, s[74:75]
	v_cndmask_b32_e64 v109, v109, v149, s[74:75]
	global_store_dwordx4 v132, v[108:111], s[68:69]
	v_cndmask_b32_e64 v42, v152, v12, s[74:75]
	v_cndmask_b32_e64 v43, v153, v13, s[74:75]
	v_cndmask_b32_e64 v40, v40, v152, s[74:75]
	v_cndmask_b32_e64 v41, v41, v153, s[74:75]
	global_store_dwordx4 v132, v[40:43], s[68:69] offset:256
	v_pk_mul_f32 v[104:105], v[104:105], v[214:215] op_sel_hi:[1,0]
	v_pk_mul_f32 v[106:107], v[106:107], v[214:215] op_sel_hi:[1,0]
	v_pk_mul_f32 v[104:105], v[180:181], v[104:105]
	v_pk_mul_f32 v[106:107], v[182:183], v[106:107]
	v_pk_fma_f32 v[104:105], v[220:221], v[104:105], v[240:241]
	v_pk_fma_f32 v[106:107], v[222:223], v[106:107], v[242:243]
	v_cvt_pk_bf16_f32 v104, v104, v105
	v_cvt_pk_bf16_f32 v105, v106, v107
	v_pk_mul_f32 v[72:73], v[72:73], v[214:215] op_sel_hi:[1,0]
	v_pk_mul_f32 v[74:75], v[74:75], v[214:215] op_sel_hi:[1,0]
	v_pk_mul_f32 v[72:73], v[184:185], v[72:73]
	v_pk_mul_f32 v[74:75], v[186:187], v[74:75]
	v_pk_fma_f32 v[72:73], v[224:225], v[72:73], v[244:245]
	v_pk_fma_f32 v[74:75], v[226:227], v[74:75], v[246:247]
	v_cvt_pk_bf16_f32 v72, v72, v73
	v_cvt_pk_bf16_f32 v73, v74, v75
	v_pk_mul_f32 v[32:33], v[32:33], v[214:215] op_sel_hi:[1,0]
	v_pk_mul_f32 v[34:35], v[34:35], v[214:215] op_sel_hi:[1,0]
	v_pk_mul_f32 v[32:33], v[188:189], v[32:33]
	v_pk_mul_f32 v[34:35], v[190:191], v[34:35]
	v_pk_fma_f32 v[32:33], v[232:233], v[32:33], v[156:157]
	v_pk_fma_f32 v[34:35], v[234:235], v[34:35], v[158:159]
	v_cvt_pk_bf16_f32 v32, v32, v33
	v_cvt_pk_bf16_f32 v33, v34, v35
	v_pk_mul_f32 v[8:9], v[8:9], v[214:215] op_sel_hi:[1,0]
	v_pk_mul_f32 v[10:11], v[10:11], v[214:215] op_sel_hi:[1,0]
	v_pk_mul_f32 v[8:9], v[192:193], v[8:9]
	v_pk_mul_f32 v[10:11], v[194:195], v[10:11]
	v_pk_fma_f32 v[8:9], v[236:237], v[8:9], v[160:161]
	v_pk_fma_f32 v[10:11], v[238:239], v[10:11], v[162:163]
	v_cvt_pk_bf16_f32 v8, v8, v9
	v_cvt_pk_bf16_f32 v9, v10, v11
	v_cndmask_b32_e64 v146, v72, v104, s[74:75]
	v_cndmask_b32_e64 v147, v73, v105, s[74:75]
	ds_bpermute_b32 v148, v137, v146
	ds_bpermute_b32 v149, v137, v147
	v_cndmask_b32_e64 v150, v8, v32, s[74:75]
	v_cndmask_b32_e64 v151, v9, v33, s[74:75]
	ds_bpermute_b32 v152, v137, v150
	ds_bpermute_b32 v153, v137, v151
	s_waitcnt lgkmcnt(0)
	v_cndmask_b32_e64 v106, v148, v72, s[74:75]
	v_cndmask_b32_e64 v107, v149, v73, s[74:75]
	v_cndmask_b32_e64 v104, v104, v148, s[74:75]
	v_cndmask_b32_e64 v105, v105, v149, s[74:75]
	global_store_dwordx4 v133, v[104:107], s[68:69]
	v_cndmask_b32_e64 v34, v152, v8, s[74:75]
	v_cndmask_b32_e64 v35, v153, v9, s[74:75]
	v_cndmask_b32_e64 v32, v32, v152, s[74:75]
	v_cndmask_b32_e64 v33, v33, v153, s[74:75]
	global_store_dwordx4 v133, v[32:35], s[68:69] offset:256
	v_pk_mul_f32 v[92:93], v[92:93], v[216:217] op_sel_hi:[1,0]
	v_pk_mul_f32 v[94:95], v[94:95], v[216:217] op_sel_hi:[1,0]
	v_pk_mul_f32 v[92:93], v[180:181], v[92:93]
	v_pk_mul_f32 v[94:95], v[182:183], v[94:95]
	v_pk_fma_f32 v[92:93], v[220:221], v[92:93], v[240:241]
	v_pk_fma_f32 v[94:95], v[222:223], v[94:95], v[242:243]
	v_cvt_pk_bf16_f32 v92, v92, v93
	v_cvt_pk_bf16_f32 v93, v94, v95
	v_pk_mul_f32 v[60:61], v[60:61], v[216:217] op_sel_hi:[1,0]
	v_pk_mul_f32 v[62:63], v[62:63], v[216:217] op_sel_hi:[1,0]
	v_pk_mul_f32 v[60:61], v[184:185], v[60:61]
	v_pk_mul_f32 v[62:63], v[186:187], v[62:63]
	v_pk_fma_f32 v[60:61], v[224:225], v[60:61], v[244:245]
	v_pk_fma_f32 v[62:63], v[226:227], v[62:63], v[246:247]
	v_cvt_pk_bf16_f32 v60, v60, v61
	v_cvt_pk_bf16_f32 v61, v62, v63
	v_pk_mul_f32 v[24:25], v[24:25], v[216:217] op_sel_hi:[1,0]
	v_pk_mul_f32 v[26:27], v[26:27], v[216:217] op_sel_hi:[1,0]
	v_pk_mul_f32 v[24:25], v[188:189], v[24:25]
	v_pk_mul_f32 v[26:27], v[190:191], v[26:27]
	v_pk_fma_f32 v[24:25], v[232:233], v[24:25], v[156:157]
	v_pk_fma_f32 v[26:27], v[234:235], v[26:27], v[158:159]
	v_cvt_pk_bf16_f32 v24, v24, v25
	v_cvt_pk_bf16_f32 v25, v26, v27
	v_pk_mul_f32 v[4:5], v[4:5], v[216:217] op_sel_hi:[1,0]
	v_pk_mul_f32 v[6:7], v[6:7], v[216:217] op_sel_hi:[1,0]
	v_pk_mul_f32 v[4:5], v[192:193], v[4:5]
	v_pk_mul_f32 v[6:7], v[194:195], v[6:7]
	v_pk_fma_f32 v[4:5], v[236:237], v[4:5], v[160:161]
	v_pk_fma_f32 v[6:7], v[238:239], v[6:7], v[162:163]
	v_cvt_pk_bf16_f32 v4, v4, v5
	v_cvt_pk_bf16_f32 v5, v6, v7
	v_cndmask_b32_e64 v146, v60, v92, s[74:75]
	v_cndmask_b32_e64 v147, v61, v93, s[74:75]
	ds_bpermute_b32 v148, v137, v146
	ds_bpermute_b32 v149, v137, v147
	v_cndmask_b32_e64 v150, v4, v24, s[74:75]
	v_cndmask_b32_e64 v151, v5, v25, s[74:75]
	ds_bpermute_b32 v152, v137, v150
	ds_bpermute_b32 v153, v137, v151
	s_waitcnt lgkmcnt(0)
	v_cndmask_b32_e64 v94, v148, v60, s[74:75]
	v_cndmask_b32_e64 v95, v149, v61, s[74:75]
	v_cndmask_b32_e64 v92, v92, v148, s[74:75]
	v_cndmask_b32_e64 v93, v93, v149, s[74:75]
	global_store_dwordx4 v134, v[92:95], s[68:69]
	v_cndmask_b32_e64 v26, v152, v4, s[74:75]
	v_cndmask_b32_e64 v27, v153, v5, s[74:75]
	v_cndmask_b32_e64 v24, v24, v152, s[74:75]
	v_cndmask_b32_e64 v25, v25, v153, s[74:75]
	global_store_dwordx4 v134, v[24:27], s[68:69] offset:256
	v_pk_mul_f32 v[84:85], v[84:85], v[218:219] op_sel_hi:[1,0]
	v_pk_mul_f32 v[86:87], v[86:87], v[218:219] op_sel_hi:[1,0]
	v_pk_mul_f32 v[84:85], v[180:181], v[84:85]
	v_pk_mul_f32 v[86:87], v[182:183], v[86:87]
	v_pk_fma_f32 v[84:85], v[220:221], v[84:85], v[240:241]
	v_pk_fma_f32 v[86:87], v[222:223], v[86:87], v[242:243]
	v_cvt_pk_bf16_f32 v84, v84, v85
	v_cvt_pk_bf16_f32 v85, v86, v87
	v_pk_mul_f32 v[56:57], v[56:57], v[218:219] op_sel_hi:[1,0]
	v_pk_mul_f32 v[58:59], v[58:59], v[218:219] op_sel_hi:[1,0]
	v_pk_mul_f32 v[56:57], v[184:185], v[56:57]
	v_pk_mul_f32 v[58:59], v[186:187], v[58:59]
	v_pk_fma_f32 v[56:57], v[224:225], v[56:57], v[244:245]
	v_pk_fma_f32 v[58:59], v[226:227], v[58:59], v[246:247]
	v_cvt_pk_bf16_f32 v56, v56, v57
	v_cvt_pk_bf16_f32 v57, v58, v59
	v_pk_mul_f32 v[16:17], v[16:17], v[218:219] op_sel_hi:[1,0]
	v_pk_mul_f32 v[18:19], v[18:19], v[218:219] op_sel_hi:[1,0]
	v_pk_mul_f32 v[16:17], v[188:189], v[16:17]
	v_pk_mul_f32 v[18:19], v[190:191], v[18:19]
	v_pk_fma_f32 v[16:17], v[232:233], v[16:17], v[156:157]
	v_pk_fma_f32 v[18:19], v[234:235], v[18:19], v[158:159]
	v_cvt_pk_bf16_f32 v16, v16, v17
	v_cvt_pk_bf16_f32 v17, v18, v19
	v_pk_mul_f32 v[0:1], v[0:1], v[218:219] op_sel_hi:[1,0]
	v_pk_mul_f32 v[2:3], v[2:3], v[218:219] op_sel_hi:[1,0]
	v_pk_mul_f32 v[0:1], v[192:193], v[0:1]
	v_pk_mul_f32 v[2:3], v[194:195], v[2:3]
	v_pk_fma_f32 v[0:1], v[236:237], v[0:1], v[160:161]
	v_pk_fma_f32 v[2:3], v[238:239], v[2:3], v[162:163]
	v_cvt_pk_bf16_f32 v0, v0, v1
	v_cvt_pk_bf16_f32 v1, v2, v3
	v_cndmask_b32_e64 v146, v56, v84, s[74:75]
	v_cndmask_b32_e64 v147, v57, v85, s[74:75]
	ds_bpermute_b32 v148, v137, v146
	ds_bpermute_b32 v149, v137, v147
	v_cndmask_b32_e64 v150, v0, v16, s[74:75]
	v_cndmask_b32_e64 v151, v1, v17, s[74:75]
	ds_bpermute_b32 v152, v137, v150
	ds_bpermute_b32 v153, v137, v151
	s_waitcnt lgkmcnt(0)
	v_cndmask_b32_e64 v86, v148, v56, s[74:75]
	v_cndmask_b32_e64 v87, v149, v57, s[74:75]
	v_cndmask_b32_e64 v84, v84, v148, s[74:75]
	v_cndmask_b32_e64 v85, v85, v149, s[74:75]
	global_store_dwordx4 v135, v[84:87], s[68:69]
	v_cndmask_b32_e64 v18, v152, v0, s[74:75]
	v_cndmask_b32_e64 v19, v153, v1, s[74:75]
	v_cndmask_b32_e64 v16, v16, v152, s[74:75]
	v_cndmask_b32_e64 v17, v17, v153, s[74:75]
	global_store_dwordx4 v135, v[16:19], s[68:69] offset:256
	s_mov_b64 s[38:39], -1
	s_andn2_b64 vcc, exec, s[6:7]
	s_cbranch_vccnz .LBB0_1192
	s_andn2_b64 vcc, exec, s[0:1]
	s_cbranch_vccnz .LBB0_1191
	s_barrier
	s_branch .LBB0_1191
